# prologue x to bf16 copy: eight 16-byte loads in flight per lane per trip instead of one load followed by a full wait
# speedup vs baseline: 1.0007x; 1.0007x over previous
; DI u32x2 pk4(float a, float b, float c, float d) { u32x2 r; r.x = pk2(a, b); r.y = pk2(c, d); return r; }
;     ...
;         const f32x4* xs = (const f32x4*)P.x; f32x4* xo = (f32x4*)P.out; u32x2* xb = (u32x2*)(P.ws + OFF_XB);
;         const int n4 = TT * DM / 4;
;         for (int i = vb * NTH + tid; i < n4; i += nb * NTH) { f32x4 v = xs[i]; xb[i] = pk4(v.x, v.y, v.z, v.w); }
;         (void)xo;
.LBB0_161:
	s_waitcnt lgkmcnt(0)
	s_load_dwordx2 s[6:7], s[0:1], 0xd8
	s_lshl_b32 s16, s60, 9
	v_add_u32_e32 v6, s16, v1
	s_mov_b32 s4, 0x800000
	v_cmp_gt_i32_e32 vcc, s4, v6
	v_ashrrev_i32_e32 v7, 31, v6
	s_and_saveexec_b64 s[4:5], vcc
	s_cbranch_execz .LBB0_164
	s_load_dwordx2 s[12:13], s[0:1], 0x0
	s_lshl_b32 s8, s96, 9
	s_waitcnt lgkmcnt(0)
	v_lshl_add_u64 v[10:11], v[6:7], 3, s[6:7]
	s_ashr_i32 s9, s8, 31
	s_lshl_b64 s[10:11], s[8:9], 4
	v_lshl_add_u64 v[8:9], v[6:7], 4, s[12:13]
	s_mov_b64 s[12:13], 0x8800000
	v_lshl_add_u64 v[10:11], v[10:11], 0, s[12:13]
	s_lshl_b64 s[12:13], s[8:9], 3
	s_mov_b64 s[14:15], 0
	s_mov_b32 s9, 0x7fffff
	v_mov_b32_e32 v3, v6
	s_mul_i32 s98, s8, 7
	s_mov_b32 s99, 0x800000
	s_mov_b64 s[100:101], exec
.Lxb8_loop:
	v_add_u32_e32 v12, s98, v3
	v_cmp_gt_i32_e32 vcc, s99, v12
	s_and_b64 exec, exec, vcc
	s_cbranch_execz .Lxb8_done
	v_lshl_add_u64 v[48:49], v[8:9], 0, s[10:11]
	v_lshl_add_u64 v[50:51], v[48:49], 0, s[10:11]
	v_lshl_add_u64 v[52:53], v[50:51], 0, s[10:11]
	v_lshl_add_u64 v[54:55], v[52:53], 0, s[10:11]
	v_lshl_add_u64 v[56:57], v[54:55], 0, s[10:11]
	v_lshl_add_u64 v[58:59], v[56:57], 0, s[10:11]
	v_lshl_add_u64 v[60:61], v[58:59], 0, s[10:11]
	global_load_dwordx4 v[16:19], v[8:9], off
	global_load_dwordx4 v[20:23], v[48:49], off
	global_load_dwordx4 v[24:27], v[50:51], off
	global_load_dwordx4 v[28:31], v[52:53], off
	global_load_dwordx4 v[32:35], v[54:55], off
	global_load_dwordx4 v[36:39], v[56:57], off
	global_load_dwordx4 v[40:43], v[58:59], off
	global_load_dwordx4 v[44:47], v[60:61], off
	v_lshl_add_u64 v[8:9], v[60:61], 0, s[10:11]
	v_lshl_add_u64 v[48:49], v[10:11], 0, s[12:13]
	v_lshl_add_u64 v[50:51], v[48:49], 0, s[12:13]
	v_lshl_add_u64 v[52:53], v[50:51], 0, s[12:13]
	v_lshl_add_u64 v[54:55], v[52:53], 0, s[12:13]
	v_lshl_add_u64 v[56:57], v[54:55], 0, s[12:13]
	v_lshl_add_u64 v[58:59], v[56:57], 0, s[12:13]
	v_lshl_add_u64 v[60:61], v[58:59], 0, s[12:13]
	v_add_u32_e32 v3, s98, v3
	v_add_u32_e32 v3, s8, v3
	s_waitcnt vmcnt(0)
	v_cvt_pk_bf16_f32 v16, v16, v17
	v_cvt_pk_bf16_f32 v17, v18, v19
	v_cvt_pk_bf16_f32 v20, v20, v21
	v_cvt_pk_bf16_f32 v21, v22, v23
	v_cvt_pk_bf16_f32 v24, v24, v25
	v_cvt_pk_bf16_f32 v25, v26, v27
	v_cvt_pk_bf16_f32 v28, v28, v29
	v_cvt_pk_bf16_f32 v29, v30, v31
	v_cvt_pk_bf16_f32 v32, v32, v33
	v_cvt_pk_bf16_f32 v33, v34, v35
	v_cvt_pk_bf16_f32 v36, v36, v37
	v_cvt_pk_bf16_f32 v37, v38, v39
	v_cvt_pk_bf16_f32 v40, v40, v41
	v_cvt_pk_bf16_f32 v41, v42, v43
	v_cvt_pk_bf16_f32 v44, v44, v45
	v_cvt_pk_bf16_f32 v45, v46, v47
	global_store_dwordx2 v[10:11], v[16:17], off
	global_store_dwordx2 v[48:49], v[20:21], off
	global_store_dwordx2 v[50:51], v[24:25], off
	global_store_dwordx2 v[52:53], v[28:29], off
	global_store_dwordx2 v[54:55], v[32:33], off
	global_store_dwordx2 v[56:57], v[36:37], off
	global_store_dwordx2 v[58:59], v[40:41], off
	global_store_dwordx2 v[60:61], v[44:45], off
	v_lshl_add_u64 v[10:11], v[60:61], 0, s[12:13]
	s_branch .Lxb8_loop
.Lxb8_done:
	s_mov_b64 exec, s[100:101]
	v_cmp_gt_i32_e32 vcc, s99, v3
	s_and_b64 exec, exec, vcc
	s_cbranch_execz .LBB0_164
